# lever 7: GEMM tile prologues zero the accumulators with v_mov_b64 (half the instructions)
# baseline (speedup 1.0000x reference)
.LBB0_145:
	s_mul_hi_i32 s6, s86, 0x78787879
	s_lshr_b32 s7, s6, 31
	s_ashr_i32 s6, s6, 6
	s_add_i32 s6, s6, s7
	s_mul_i32 s7, s6, 0x88
	s_sub_i32 s8, s86, s7
	v_mov_b32_e32 v0, v174
	s_ashr_i32 s9, s8, 31
	s_lshl_b64 s[10:11], s[8:9], 18
	v_bfe_u32 v2, v0, 1, 3
	v_lshrrev_b32_e32 v3, 4, v0
	v_bfe_u32 v4, v0, 4, 2
	v_lshlrev_b32_e32 v5, 7, v0
	v_and_b32_e32 v6, 0x780, v5
	v_bitop3_b32 v3, v3, v2, 3 bitop3:0x6c
	v_bitop3_b32 v2, v4, v2, 4 bitop3:0x36
	s_add_u32 s12, s38, s10
	v_lshl_or_b32 v7, v3, 4, v6
	v_lshl_or_b32 v6, v2, 4, v6
	v_lshlrev_b32_e32 v2, 6, v0
	s_addc_u32 s13, s39, s11
	s_ashr_i32 s7, s6, 31
	v_lshlrev_b32_e32 v1, 8, v0
	v_and_b32_e32 v8, 0xffffe000, v2
	v_lshlrev_b32_e32 v2, 4, v0
	s_lshl_b64 s[10:11], s[6:7], 18
	v_and_b32_e32 v1, 0xfffff800, v1
	v_xor_b32_e32 v0, v2, v0
	s_movk_i32 s7, 0x70
	v_add_u32_e32 v103, 0, v2
	v_and_or_b32 v64, v0, s7, v1
	v_readfirstlane_b32 s7, v103
	v_add_u32_e32 v104, 0x1000, v103
	s_mov_b32 m0, s7
	v_readfirstlane_b32 s7, v104
	v_add_u32_e32 v105, 0x2000, v103
	global_load_lds_dwordx4 v64, s[12:13]
	v_add_u32_e32 v0, 0x10000, v64
	s_mov_b32 m0, s7
	v_readfirstlane_b32 s7, v105
	v_add_u32_e32 v106, 0x3000, v103
	global_load_lds_dwordx4 v0, s[12:13]
	v_add_u32_e32 v2, 0x20000, v64
	s_mov_b32 m0, s7
	v_readfirstlane_b32 s7, v106
	v_add_u32_e32 v107, 0x4000, v103
	s_add_u32 s84, s36, s10
	global_load_lds_dwordx4 v2, s[12:13]
	v_add_u32_e32 v4, 0x30000, v64
	s_mov_b32 m0, s7
	v_readfirstlane_b32 s7, v107
	v_add_u32_e32 v108, 0x5000, v103
	s_addc_u32 s85, s37, s11
	global_load_lds_dwordx4 v4, s[12:13]
	s_mov_b32 m0, s7
	v_readfirstlane_b32 s7, v108
	v_add_u32_e32 v109, 0x6000, v103
	global_load_lds_dwordx4 v64, s[84:85]
	s_mov_b32 m0, s7
	v_readfirstlane_b32 s7, v109
	v_add_u32_e32 v110, 0x7000, v103
	global_load_lds_dwordx4 v0, s[84:85]
	s_mov_b32 m0, s7
	v_readfirstlane_b32 s7, v110
	global_load_lds_dwordx4 v2, s[84:85]
	s_mov_b32 m0, s7
	v_and_b32_e32 v9, 0x2000, v5
	global_load_lds_dwordx4 v4, s[84:85]
	v_mov_b32_e32 v1, v65
	v_lshl_add_u64 v[66:67], s[12:13], 0, v[0:1]
	v_mov_b32_e32 v3, v65
	v_mov_b32_e32 v5, v65
	v_lshl_add_u64 v[72:73], s[84:85], 0, v[0:1]
	v_add_u32_e32 v0, 0, v8
	v_add_u32_e32 v1, 0, v9
	v_lshl_add_u64 v[68:69], s[12:13], 0, v[2:3]
	v_lshl_add_u64 v[70:71], s[12:13], 0, v[4:5]
	v_lshl_add_u64 v[74:75], s[84:85], 0, v[2:3]
	v_lshl_add_u64 v[76:77], s[84:85], 0, v[4:5]
	s_mov_b64 s[10:11], 0
	v_add_u32_e32 v111, v0, v7
	v_add_u32_e32 v112, v1, v7
	v_add_u32_e32 v113, v0, v6
	v_add_u32_e32 v114, v1, v6
	s_mov_b32 s7, 0
	v_mov_b64_e32 v[0:1], 0
	v_mov_b32_e32 v2, 0
	v_mov_b32_e32 v4, 0
	v_mov_b64_e32 v[6:7], 0
	v_mov_b64_e32 v[8:9], 0
	v_mov_b64_e32 v[10:11], 0
	v_mov_b64_e32 v[12:13], 0
	v_mov_b64_e32 v[14:15], 0
	v_mov_b64_e32 v[16:17], 0
	v_mov_b64_e32 v[18:19], 0
	v_mov_b64_e32 v[20:21], 0
	v_mov_b64_e32 v[22:23], 0
	v_mov_b64_e32 v[24:25], 0
	v_mov_b64_e32 v[26:27], 0
	v_mov_b64_e32 v[28:29], 0
	v_mov_b64_e32 v[30:31], 0
	v_mov_b64_e32 v[32:33], 0
	v_mov_b64_e32 v[34:35], 0
	v_mov_b64_e32 v[36:37], 0
	v_mov_b64_e32 v[38:39], 0
	v_mov_b64_e32 v[40:41], 0
	v_mov_b64_e32 v[42:43], 0
	v_mov_b64_e32 v[44:45], 0
	v_mov_b64_e32 v[46:47], 0
	v_mov_b64_e32 v[48:49], 0
	v_mov_b64_e32 v[50:51], 0
	v_mov_b64_e32 v[52:53], 0
	v_mov_b64_e32 v[54:55], 0
	v_mov_b64_e32 v[56:57], 0
	v_mov_b64_e32 v[58:59], 0
	v_mov_b64_e32 v[60:61], 0
	v_mov_b64_e32 v[62:63], 0
	v_add_u32_e32 v115, 0x8000, v103
	v_add_u32_e32 v116, 0x9000, v103
	v_add_u32_e32 v117, 0xa000, v103
	v_add_u32_e32 v118, 0xb000, v103
	v_add_u32_e32 v119, 0xc000, v103
	v_add_u32_e32 v120, 0xd000, v103
	v_add_u32_e32 v121, 0xe000, v103
	v_add_u32_e32 v122, 0xf000, v103
	v_lshl_add_u64 v[78:79], s[12:13], 0, v[64:65]
	v_lshl_add_u64 v[80:81], s[84:85], 0, v[64:65]
	s_branch .LBB0_147

.Lto_j_a0:
	s_mul_i32 s98, s98, 17
	s_add_u32 s98, s98, s99
	s_lshl_b32 s99, s98, 3
	s_or_b32 s99, s99, s84
	s_mul_hi_i32 s6, s98, 0x78787879
	s_lshr_b32 s7, s6, 31
	s_ashr_i32 s6, s6, 3
	s_add_i32 s6, s6, s7
	s_mul_i32 s7, s6, 0xffffffef
	s_add_i32 s7, s7, s98
	s_lshl_b32 s7, s7, 3
	s_or_b32 s8, s7, s84
	v_mov_b32_e32 v0, v174
	s_ashr_i32 s9, s8, 31
	s_lshl_b64 s[10:11], s[8:9], 18
	v_bfe_u32 v2, v0, 1, 3
	v_lshrrev_b32_e32 v3, 4, v0
	v_bfe_u32 v4, v0, 4, 2
	v_lshlrev_b32_e32 v5, 7, v0
	v_and_b32_e32 v6, 0x780, v5
	v_bitop3_b32 v3, v3, v2, 3 bitop3:0x6c
	v_bitop3_b32 v2, v4, v2, 4 bitop3:0x36
	s_add_u32 s10, s38, s10
	v_lshl_or_b32 v7, v3, 4, v6
	v_lshl_or_b32 v6, v2, 4, v6
	v_lshlrev_b32_e32 v2, 6, v0
	s_addc_u32 s11, s39, s11
	s_ashr_i32 s7, s6, 31
	v_lshlrev_b32_e32 v1, 8, v0
	v_and_b32_e32 v8, 0xffffe000, v2
	v_lshlrev_b32_e32 v2, 4, v0
	s_lshl_b64 s[12:13], s[6:7], 18
	v_and_b32_e32 v1, 0xfffff800, v1
	v_xor_b32_e32 v0, v2, v0
	s_movk_i32 s7, 0x70
	v_add_u32_e32 v100, 0, v2
	v_and_or_b32 v64, v0, s7, v1
	v_readfirstlane_b32 s7, v100
	v_add_u32_e32 v101, 0x1000, v100
	s_mov_b32 m0, s7
	v_readfirstlane_b32 s7, v101
	v_add_u32_e32 v102, 0x2000, v100
	global_load_lds_dwordx4 v64, s[10:11]
	v_add_u32_e32 v0, 0x10000, v64
	s_mov_b32 m0, s7
	v_readfirstlane_b32 s7, v102
	v_add_u32_e32 v103, 0x3000, v100
	global_load_lds_dwordx4 v0, s[10:11]
	v_add_u32_e32 v2, 0x20000, v64
	s_mov_b32 m0, s7
	v_readfirstlane_b32 s7, v103
	v_add_u32_e32 v104, 0x4000, v100
	s_add_u32 s12, s36, s12
	global_load_lds_dwordx4 v2, s[10:11]
	v_add_u32_e32 v4, 0x30000, v64
	s_mov_b32 m0, s7
	v_readfirstlane_b32 s7, v104
	v_add_u32_e32 v105, 0x5000, v100
	s_addc_u32 s13, s37, s13
	global_load_lds_dwordx4 v4, s[10:11]
	s_mov_b32 m0, s7
	v_readfirstlane_b32 s7, v105
	v_add_u32_e32 v106, 0x6000, v100
	global_load_lds_dwordx4 v64, s[12:13]
	s_mov_b32 m0, s7
	v_readfirstlane_b32 s7, v106
	v_add_u32_e32 v107, 0x7000, v100
	global_load_lds_dwordx4 v0, s[12:13]
	s_mov_b32 m0, s7
	v_readfirstlane_b32 s7, v107
	global_load_lds_dwordx4 v2, s[12:13]
	s_mov_b32 m0, s7
	s_mul_i32 s7, s6, 0x88
	global_load_lds_dwordx4 v4, s[12:13]
	s_sub_i32 s10, s99, s7
	s_ashr_i32 s11, s10, 31
	s_lshl_b64 s[10:11], s[10:11], 18
	v_and_b32_e32 v9, 0x2000, v5
	s_add_u32 s10, s38, s10
	v_mov_b32_e32 v1, v65
	v_mov_b32_e32 v3, v65
	v_mov_b32_e32 v5, v65
	v_add_u32_e32 v8, 0, v8
	v_add_u32_e32 v9, 0, v9
	s_addc_u32 s11, s39, s11
	v_lshl_add_u64 v[66:67], s[12:13], 0, v[64:65]
	v_lshl_add_u64 v[68:69], s[12:13], 0, v[0:1]
	v_lshl_add_u64 v[70:71], s[12:13], 0, v[2:3]
	v_lshl_add_u64 v[72:73], s[12:13], 0, v[4:5]
	v_lshl_add_u64 v[74:75], s[10:11], 0, v[64:65]
	v_lshl_add_u64 v[76:77], s[10:11], 0, v[0:1]
	v_lshl_add_u64 v[78:79], s[10:11], 0, v[2:3]
	v_lshl_add_u64 v[80:81], s[10:11], 0, v[4:5]
	s_mov_b64 s[10:11], 0
	v_add_u32_e32 v64, 0x8000, v100
	v_add_u32_e32 v108, 0x9000, v100
	v_add_u32_e32 v109, 0xa000, v100
	v_add_u32_e32 v110, 0xb000, v100
	v_add_u32_e32 v111, 0xc000, v100
	v_add_u32_e32 v112, 0xd000, v100
	v_add_u32_e32 v113, 0xe000, v100
	v_add_u32_e32 v114, 0xf000, v100
	v_add_u32_e32 v115, v8, v7
	v_add_u32_e32 v116, v9, v7
	v_add_u32_e32 v117, v8, v6
	v_add_u32_e32 v118, v9, v6
	s_mov_b32 s7, 0
	v_mov_b32_e32 v0, 0
	v_mov_b32_e32 v2, 0
	v_mov_b32_e32 v4, 0
	v_mov_b64_e32 v[6:7], 0
	v_mov_b64_e32 v[8:9], 0
	v_mov_b64_e32 v[10:11], 0
	v_mov_b64_e32 v[12:13], 0
	v_mov_b64_e32 v[14:15], 0
	v_mov_b64_e32 v[16:17], 0
	v_mov_b64_e32 v[18:19], 0
	v_mov_b64_e32 v[20:21], 0
	v_mov_b64_e32 v[22:23], 0
	v_mov_b64_e32 v[24:25], 0
	v_mov_b64_e32 v[26:27], 0
	v_mov_b64_e32 v[28:29], 0
	v_mov_b64_e32 v[30:31], 0
	v_mov_b64_e32 v[32:33], 0
	v_mov_b64_e32 v[34:35], 0
	v_mov_b64_e32 v[36:37], 0
	v_mov_b64_e32 v[38:39], 0
	v_mov_b64_e32 v[40:41], 0
	v_mov_b64_e32 v[42:43], 0
	v_mov_b64_e32 v[44:45], 0
	v_mov_b64_e32 v[46:47], 0
	v_mov_b64_e32 v[48:49], 0
	v_mov_b64_e32 v[50:51], 0
	v_mov_b64_e32 v[52:53], 0
	v_mov_b64_e32 v[54:55], 0
	v_mov_b64_e32 v[56:57], 0
	v_mov_b64_e32 v[58:59], 0
	v_mov_b64_e32 v[60:61], 0
	v_mov_b64_e32 v[62:63], 0
	s_nop 1
	v_readfirstlane_b32 s10, v74
	v_readfirstlane_b32 s11, v75
	v_readfirstlane_b32 s98, v66
	v_readfirstlane_b32 s99, v67
	v_readfirstlane_b32 s100, v100
	s_nop 1
	s_sub_u32 s10, s10, 0x80
	s_subb_u32 s11, s11, 0
	s_sub_u32 s98, s98, 0x80
	s_subb_u32 s99, s99, 0
	v_subrev_u32_e32 v74, s10, v74
	v_subrev_u32_e32 v76, s10, v76
	v_subrev_u32_e32 v78, s10, v78
	v_subrev_u32_e32 v80, s10, v80
	v_subrev_u32_e32 v66, s98, v66
	v_subrev_u32_e32 v68, s98, v68
	v_subrev_u32_e32 v70, s98, v70
	v_subrev_u32_e32 v72, s98, v72
	s_add_u32 s10, s10, 0x80
	s_addc_u32 s11, s11, 0x0
	s_add_u32 s98, s98, 0x80
	s_addc_u32 s99, s99, 0x0
	s_branch .LBB0_156

.LBB0_599:
	s_mul_hi_i32 s10, s89, 0x78787879
	s_lshr_b32 s11, s10, 31
	s_ashr_i32 s10, s10, 6
	s_add_i32 s10, s10, s11
	s_mul_i32 s11, s10, 0x88
	s_sub_i32 s12, s89, s11
	v_mov_b32_e32 v0, v174
	s_ashr_i32 s13, s12, 31
	s_lshl_b64 s[34:35], s[12:13], 18
	v_bfe_u32 v2, v0, 1, 3
	v_lshrrev_b32_e32 v3, 4, v0
	v_bfe_u32 v4, v0, 4, 2
	v_lshlrev_b32_e32 v5, 7, v0
	v_and_b32_e32 v6, 0x780, v5
	v_bitop3_b32 v3, v3, v2, 3 bitop3:0x6c
	v_bitop3_b32 v2, v4, v2, 4 bitop3:0x36
	s_add_u32 s34, s38, s34
	v_lshl_or_b32 v7, v3, 4, v6
	v_lshl_or_b32 v6, v2, 4, v6
	v_lshlrev_b32_e32 v2, 6, v0
	s_addc_u32 s35, s39, s35
	s_ashr_i32 s11, s10, 31
	v_lshlrev_b32_e32 v1, 8, v0
	v_and_b32_e32 v8, 0xffffe000, v2
	v_lshlrev_b32_e32 v2, 4, v0
	s_lshl_b64 s[84:85], s[10:11], 18
	v_and_b32_e32 v1, 0xfffff800, v1
	v_xor_b32_e32 v0, v2, v0
	s_movk_i32 s11, 0x70
	v_add_u32_e32 v103, 0, v2
	v_and_or_b32 v64, v0, s11, v1
	v_readfirstlane_b32 s11, v103
	v_add_u32_e32 v104, 0x1000, v103
	s_mov_b32 m0, s11
	v_readfirstlane_b32 s11, v104
	v_add_u32_e32 v105, 0x2000, v103
	global_load_lds_dwordx4 v64, s[34:35]
	v_add_u32_e32 v0, 0x10000, v64
	s_mov_b32 m0, s11
	v_readfirstlane_b32 s11, v105
	v_add_u32_e32 v106, 0x3000, v103
	global_load_lds_dwordx4 v0, s[34:35]
	v_add_u32_e32 v2, 0x20000, v64
	s_mov_b32 m0, s11
	v_readfirstlane_b32 s11, v106
	v_add_u32_e32 v107, 0x4000, v103
	s_add_u32 s86, s3, s84
	global_load_lds_dwordx4 v2, s[34:35]
	v_add_u32_e32 v4, 0x30000, v64
	s_mov_b32 m0, s11
	v_readfirstlane_b32 s11, v107
	v_add_u32_e32 v108, 0x5000, v103
	s_addc_u32 s87, s88, s85
	global_load_lds_dwordx4 v4, s[34:35]
	s_mov_b32 m0, s11
	v_readfirstlane_b32 s11, v108
	v_add_u32_e32 v109, 0x6000, v103
	global_load_lds_dwordx4 v64, s[86:87]
	s_mov_b32 m0, s11
	v_readfirstlane_b32 s11, v109
	v_add_u32_e32 v110, 0x7000, v103
	global_load_lds_dwordx4 v0, s[86:87]
	s_mov_b32 m0, s11
	v_readfirstlane_b32 s11, v110
	global_load_lds_dwordx4 v2, s[86:87]
	s_mov_b32 m0, s11
	v_and_b32_e32 v9, 0x2000, v5
	global_load_lds_dwordx4 v4, s[86:87]
	v_mov_b32_e32 v1, v65
	v_mov_b32_e32 v3, v65
	v_mov_b32_e32 v5, v65
	v_lshl_add_u64 v[66:67], s[34:35], 0, v[64:65]
	v_lshl_add_u64 v[68:69], s[34:35], 0, v[0:1]
	v_lshl_add_u64 v[70:71], s[34:35], 0, v[2:3]
	v_lshl_add_u64 v[72:73], s[34:35], 0, v[4:5]
	s_add_u32 s34, s36, s84
	v_add_u32_e32 v8, 0, v8
	v_add_u32_e32 v9, 0, v9
	s_addc_u32 s35, s37, s85
	v_lshl_add_u64 v[74:75], s[34:35], 0, v[64:65]
	v_lshl_add_u64 v[76:77], s[34:35], 0, v[0:1]
	v_lshl_add_u64 v[78:79], s[34:35], 0, v[2:3]
	v_lshl_add_u64 v[80:81], s[34:35], 0, v[4:5]
	s_mov_b64 s[84:85], 0
	v_add_u32_e32 v64, 0x8000, v103
	v_add_u32_e32 v111, 0x9000, v103
	v_add_u32_e32 v112, 0xa000, v103
	v_add_u32_e32 v113, 0xb000, v103
	v_add_u32_e32 v114, 0xc000, v103
	v_add_u32_e32 v115, 0xd000, v103
	v_add_u32_e32 v116, 0xe000, v103
	v_add_u32_e32 v117, 0xf000, v103
	v_add_u32_e32 v118, v8, v7
	v_add_u32_e32 v119, v9, v7
	v_add_u32_e32 v120, v8, v6
	v_add_u32_e32 v121, v9, v6
	s_mov_b32 s11, 0
	v_mov_b32_e32 v0, 0
	v_mov_b32_e32 v2, 0
	v_mov_b32_e32 v4, 0
	v_mov_b64_e32 v[6:7], 0
	v_mov_b64_e32 v[8:9], 0
	v_mov_b64_e32 v[10:11], 0
	v_mov_b64_e32 v[12:13], 0
	v_mov_b64_e32 v[14:15], 0
	v_mov_b64_e32 v[16:17], 0
	v_mov_b64_e32 v[18:19], 0
	v_mov_b64_e32 v[20:21], 0
	v_mov_b64_e32 v[22:23], 0
	v_mov_b64_e32 v[24:25], 0
	v_mov_b64_e32 v[26:27], 0
	v_mov_b64_e32 v[28:29], 0
	v_mov_b64_e32 v[30:31], 0
	v_mov_b64_e32 v[32:33], 0
	v_mov_b64_e32 v[34:35], 0
	v_mov_b64_e32 v[36:37], 0
	v_mov_b64_e32 v[38:39], 0
	v_mov_b64_e32 v[40:41], 0
	v_mov_b64_e32 v[42:43], 0
	v_mov_b64_e32 v[44:45], 0
	v_mov_b64_e32 v[46:47], 0
	v_mov_b64_e32 v[48:49], 0
	v_mov_b64_e32 v[50:51], 0
	v_mov_b64_e32 v[52:53], 0
	v_mov_b64_e32 v[54:55], 0
	v_mov_b64_e32 v[56:57], 0
	v_mov_b64_e32 v[58:59], 0
	v_mov_b64_e32 v[60:61], 0
	v_mov_b64_e32 v[62:63], 0
	s_branch .LBB0_601

.LBB0_608:
	s_lshr_b32 s98, s3, 3
	s_and_b32 s99, s3, 7
	s_and_b32 s100, s88, 1
	s_lshl_b32 s98, s98, 1
	s_or_b32 s98, s98, s100
	s_lshr_b32 s100, s88, 1
	s_lshl_b32 s99, s99, 2
	s_or_b32 s99, s99, s100
	s_and_b32 s101, s98, 7
	s_lshr_b32 s98, s98, 3
	s_mul_i32 s99, s99, 17
	s_add_u32 s98, s98, s99
	s_lshl_b32 s99, s98, 3
	s_or_b32 s99, s99, s101
	s_mul_hi_i32 s10, s98, 0x78787879
	s_lshr_b32 s11, s10, 31
	s_ashr_i32 s10, s10, 3
	s_add_i32 s10, s10, s11
	s_mul_i32 s11, s10, 0xffffffef
	s_add_i32 s11, s11, s98
	s_lshl_b32 s11, s11, 3
	s_or_b32 s12, s11, s101
	v_mov_b32_e32 v0, v174
	s_ashr_i32 s13, s12, 31
	s_lshl_b64 s[34:35], s[12:13], 18
	v_bfe_u32 v2, v0, 1, 3
	v_lshrrev_b32_e32 v3, 4, v0
	v_bfe_u32 v4, v0, 4, 2
	v_lshlrev_b32_e32 v5, 7, v0
	v_and_b32_e32 v6, 0x780, v5
	v_bitop3_b32 v3, v3, v2, 3 bitop3:0x6c
	v_bitop3_b32 v2, v4, v2, 4 bitop3:0x36
	s_add_u32 s34, s38, s34
	v_lshl_or_b32 v7, v3, 4, v6
	v_lshl_or_b32 v6, v2, 4, v6
	v_lshlrev_b32_e32 v2, 6, v0
	s_addc_u32 s35, s39, s35
	s_ashr_i32 s11, s10, 31
	v_lshlrev_b32_e32 v1, 8, v0
	v_and_b32_e32 v8, 0xffffe000, v2
	v_lshlrev_b32_e32 v2, 4, v0
	s_lshl_b64 s[84:85], s[10:11], 18
	v_and_b32_e32 v1, 0xfffff800, v1
	v_xor_b32_e32 v0, v2, v0
	s_movk_i32 s11, 0x70
	v_add_u32_e32 v100, 0, v2
	v_and_or_b32 v64, v0, s11, v1
	v_readfirstlane_b32 s11, v100
	v_add_u32_e32 v101, 0x1000, v100
	s_mov_b32 m0, s11
	v_readfirstlane_b32 s11, v101
	v_add_u32_e32 v102, 0x2000, v100
	global_load_lds_dwordx4 v64, s[34:35]
	v_add_u32_e32 v0, 0x10000, v64
	s_mov_b32 m0, s11
	v_readfirstlane_b32 s11, v102
	v_add_u32_e32 v103, 0x3000, v100
	global_load_lds_dwordx4 v0, s[34:35]
	v_add_u32_e32 v2, 0x20000, v64
	s_mov_b32 m0, s11
	v_readfirstlane_b32 s11, v103
	v_add_u32_e32 v104, 0x4000, v100
	s_add_u32 s86, s90, s84
	global_load_lds_dwordx4 v2, s[34:35]
	v_add_u32_e32 v4, 0x30000, v64
	s_mov_b32 m0, s11
	v_readfirstlane_b32 s11, v104
	v_add_u32_e32 v105, 0x5000, v100
	s_addc_u32 s87, s91, s85
	global_load_lds_dwordx4 v4, s[34:35]
	s_mov_b32 m0, s11
	v_readfirstlane_b32 s11, v105
	v_add_u32_e32 v106, 0x6000, v100
	global_load_lds_dwordx4 v64, s[86:87]
	s_mov_b32 m0, s11
	v_readfirstlane_b32 s11, v106
	v_add_u32_e32 v107, 0x7000, v100
	global_load_lds_dwordx4 v0, s[86:87]
	s_mov_b32 m0, s11
	v_readfirstlane_b32 s11, v107
	global_load_lds_dwordx4 v2, s[86:87]
	s_mov_b32 m0, s11
	s_mul_i32 s11, s10, 0x88
	global_load_lds_dwordx4 v4, s[86:87]
	s_sub_i32 s34, s99, s11
	s_ashr_i32 s35, s34, 31
	s_lshl_b64 s[34:35], s[34:35], 18
	s_add_u32 s34, s38, s34
	v_and_b32_e32 v9, 0x2000, v5
	v_mov_b32_e32 v1, v65
	v_mov_b32_e32 v3, v65
	v_mov_b32_e32 v5, v65
	s_addc_u32 s35, s39, s35
	v_lshl_add_u64 v[66:67], s[34:35], 0, v[64:65]
	v_lshl_add_u64 v[68:69], s[34:35], 0, v[0:1]
	v_lshl_add_u64 v[70:71], s[34:35], 0, v[2:3]
	v_lshl_add_u64 v[72:73], s[34:35], 0, v[4:5]
	s_add_u32 s34, s36, s84
	v_add_u32_e32 v8, 0, v8
	v_add_u32_e32 v9, 0, v9
	s_addc_u32 s35, s37, s85
	v_lshl_add_u64 v[74:75], s[34:35], 0, v[64:65]
	v_lshl_add_u64 v[76:77], s[34:35], 0, v[0:1]
	v_lshl_add_u64 v[78:79], s[34:35], 0, v[2:3]
	v_lshl_add_u64 v[80:81], s[34:35], 0, v[4:5]
	s_mov_b64 s[84:85], 0
	v_add_u32_e32 v64, 0x8000, v100
	v_add_u32_e32 v108, 0x9000, v100
	v_add_u32_e32 v109, 0xa000, v100
	v_add_u32_e32 v110, 0xb000, v100
	v_add_u32_e32 v111, 0xc000, v100
	v_add_u32_e32 v112, 0xd000, v100
	v_add_u32_e32 v113, 0xe000, v100
	v_add_u32_e32 v114, 0xf000, v100
	v_add_u32_e32 v115, v8, v7
	v_add_u32_e32 v116, v9, v7
	v_add_u32_e32 v117, v8, v6
	v_add_u32_e32 v118, v9, v6
	s_mov_b32 s11, 0
	v_mov_b32_e32 v0, 0
	v_mov_b32_e32 v2, 0
	v_mov_b32_e32 v4, 0
	v_mov_b64_e32 v[6:7], 0
	v_mov_b64_e32 v[8:9], 0
	v_mov_b64_e32 v[10:11], 0
	v_mov_b64_e32 v[12:13], 0
	v_mov_b64_e32 v[14:15], 0
	v_mov_b64_e32 v[16:17], 0
	v_mov_b64_e32 v[18:19], 0
	v_mov_b64_e32 v[20:21], 0
	v_mov_b64_e32 v[22:23], 0
	v_mov_b64_e32 v[24:25], 0
	v_mov_b64_e32 v[26:27], 0
	v_mov_b64_e32 v[28:29], 0
	v_mov_b64_e32 v[30:31], 0
	v_mov_b64_e32 v[32:33], 0
	v_mov_b64_e32 v[34:35], 0
	v_mov_b64_e32 v[36:37], 0
	v_mov_b64_e32 v[38:39], 0
	v_mov_b64_e32 v[40:41], 0
	v_mov_b64_e32 v[42:43], 0
	v_mov_b64_e32 v[44:45], 0
	v_mov_b64_e32 v[46:47], 0
	v_mov_b64_e32 v[48:49], 0
	v_mov_b64_e32 v[50:51], 0
	v_mov_b64_e32 v[52:53], 0
	v_mov_b64_e32 v[54:55], 0
	v_mov_b64_e32 v[56:57], 0
	v_mov_b64_e32 v[58:59], 0
	v_mov_b64_e32 v[60:61], 0
	v_mov_b64_e32 v[62:63], 0
	s_nop 1
	v_readfirstlane_b32 s84, v66
	v_readfirstlane_b32 s85, v67
	v_readfirstlane_b32 s98, v74
	v_readfirstlane_b32 s99, v75
	v_readfirstlane_b32 s100, v100
	s_nop 1
	s_sub_u32 s84, s84, 0x80
	s_subb_u32 s85, s85, 0
	s_sub_u32 s98, s98, 0x80
	s_subb_u32 s99, s99, 0
	v_subrev_u32_e32 v66, s84, v66
	v_subrev_u32_e32 v68, s84, v68
	v_subrev_u32_e32 v70, s84, v70
	v_subrev_u32_e32 v72, s84, v72
	v_subrev_u32_e32 v74, s98, v74
	v_subrev_u32_e32 v76, s98, v76
	v_subrev_u32_e32 v78, s98, v78
	v_subrev_u32_e32 v80, s98, v80
	s_add_u32 s84, s84, 0x80
	s_addc_u32 s85, s85, 0x0
	s_add_u32 s98, s98, 0x7c0080
	s_addc_u32 s99, s99, 0x0
	s_branch .LBB0_610

.LBB0_873:
	s_mul_hi_i32 s10, s92, 0x78787879
	s_lshr_b32 s11, s10, 31
	s_ashr_i32 s10, s10, 6
	s_add_i32 s10, s10, s11
	s_mul_i32 s11, s10, 0x88
	s_sub_i32 s12, s92, s11
	v_mov_b32_e32 v0, v174
	s_ashr_i32 s13, s12, 31
	s_lshl_b64 s[34:35], s[12:13], 18
	v_bfe_u32 v2, v0, 1, 3
	v_lshrrev_b32_e32 v3, 4, v0
	v_bfe_u32 v4, v0, 4, 2
	v_lshlrev_b32_e32 v5, 7, v0
	v_and_b32_e32 v6, 0x780, v5
	v_bitop3_b32 v3, v3, v2, 3 bitop3:0x6c
	v_bitop3_b32 v2, v4, v2, 4 bitop3:0x36
	s_add_u32 s34, s38, s34
	v_lshl_or_b32 v7, v3, 4, v6
	v_lshl_or_b32 v6, v2, 4, v6
	v_lshlrev_b32_e32 v2, 6, v0
	s_addc_u32 s35, s39, s35
	s_ashr_i32 s11, s10, 31
	v_lshlrev_b32_e32 v1, 8, v0
	v_and_b32_e32 v8, 0xffffe000, v2
	v_lshlrev_b32_e32 v2, 4, v0
	s_lshl_b64 s[84:85], s[10:11], 18
	v_and_b32_e32 v1, 0xfffff800, v1
	v_xor_b32_e32 v0, v2, v0
	s_movk_i32 s11, 0x70
	v_add_u32_e32 v103, 0, v2
	v_and_or_b32 v64, v0, s11, v1
	v_readfirstlane_b32 s11, v103
	v_add_u32_e32 v104, 0x1000, v103
	s_mov_b32 m0, s11
	v_readfirstlane_b32 s11, v104
	v_add_u32_e32 v105, 0x2000, v103
	global_load_lds_dwordx4 v64, s[34:35]
	v_add_u32_e32 v0, 0x10000, v64
	s_mov_b32 m0, s11
	v_readfirstlane_b32 s11, v105
	v_add_u32_e32 v106, 0x3000, v103
	global_load_lds_dwordx4 v0, s[34:35]
	v_add_u32_e32 v2, 0x20000, v64
	s_mov_b32 m0, s11
	v_readfirstlane_b32 s11, v106
	v_add_u32_e32 v107, 0x4000, v103
	s_add_u32 s88, s3, s84
	global_load_lds_dwordx4 v2, s[34:35]
	v_add_u32_e32 v4, 0x30000, v64
	s_mov_b32 m0, s11
	v_readfirstlane_b32 s11, v107
	v_add_u32_e32 v108, 0x5000, v103
	s_addc_u32 s89, s90, s85
	global_load_lds_dwordx4 v4, s[34:35]
	s_mov_b32 m0, s11
	v_readfirstlane_b32 s11, v108
	v_add_u32_e32 v109, 0x6000, v103
	global_load_lds_dwordx4 v64, s[88:89]
	s_mov_b32 m0, s11
	v_readfirstlane_b32 s11, v109
	v_add_u32_e32 v110, 0x7000, v103
	global_load_lds_dwordx4 v0, s[88:89]
	s_mov_b32 m0, s11
	v_readfirstlane_b32 s11, v110
	global_load_lds_dwordx4 v2, s[88:89]
	s_mov_b32 m0, s11
	v_and_b32_e32 v9, 0x2000, v5
	global_load_lds_dwordx4 v4, s[88:89]
	v_mov_b32_e32 v1, v65
	v_mov_b32_e32 v3, v65
	v_mov_b32_e32 v5, v65
	v_lshl_add_u64 v[66:67], s[34:35], 0, v[64:65]
	v_lshl_add_u64 v[68:69], s[34:35], 0, v[0:1]
	v_lshl_add_u64 v[70:71], s[34:35], 0, v[2:3]
	v_lshl_add_u64 v[72:73], s[34:35], 0, v[4:5]
	s_add_u32 s34, s36, s84
	v_add_u32_e32 v8, 0, v8
	v_add_u32_e32 v9, 0, v9
	s_addc_u32 s35, s37, s85
	v_lshl_add_u64 v[74:75], s[34:35], 0, v[64:65]
	v_lshl_add_u64 v[76:77], s[34:35], 0, v[0:1]
	v_lshl_add_u64 v[78:79], s[34:35], 0, v[2:3]
	v_lshl_add_u64 v[80:81], s[34:35], 0, v[4:5]
	s_mov_b64 s[84:85], 0
	v_add_u32_e32 v64, 0x8000, v103
	v_add_u32_e32 v111, 0x9000, v103
	v_add_u32_e32 v112, 0xa000, v103
	v_add_u32_e32 v113, 0xb000, v103
	v_add_u32_e32 v114, 0xc000, v103
	v_add_u32_e32 v115, 0xd000, v103
	v_add_u32_e32 v116, 0xe000, v103
	v_add_u32_e32 v117, 0xf000, v103
	v_add_u32_e32 v118, v8, v7
	v_add_u32_e32 v119, v9, v7
	v_add_u32_e32 v120, v8, v6
	v_add_u32_e32 v121, v9, v6
	s_mov_b32 s11, 0
	v_mov_b32_e32 v0, 0
	v_mov_b32_e32 v2, 0
	v_mov_b32_e32 v4, 0
	v_mov_b64_e32 v[6:7], 0
	v_mov_b64_e32 v[8:9], 0
	v_mov_b64_e32 v[10:11], 0
	v_mov_b64_e32 v[12:13], 0
	v_mov_b64_e32 v[14:15], 0
	v_mov_b64_e32 v[16:17], 0
	v_mov_b64_e32 v[18:19], 0
	v_mov_b64_e32 v[20:21], 0
	v_mov_b64_e32 v[22:23], 0
	v_mov_b64_e32 v[24:25], 0
	v_mov_b64_e32 v[26:27], 0
	v_mov_b64_e32 v[28:29], 0
	v_mov_b64_e32 v[30:31], 0
	v_mov_b64_e32 v[32:33], 0
	v_mov_b64_e32 v[34:35], 0
	v_mov_b64_e32 v[36:37], 0
	v_mov_b64_e32 v[38:39], 0
	v_mov_b64_e32 v[40:41], 0
	v_mov_b64_e32 v[42:43], 0
	v_mov_b64_e32 v[44:45], 0
	v_mov_b64_e32 v[46:47], 0
	v_mov_b64_e32 v[48:49], 0
	v_mov_b64_e32 v[50:51], 0
	v_mov_b64_e32 v[52:53], 0
	v_mov_b64_e32 v[54:55], 0
	v_mov_b64_e32 v[56:57], 0
	v_mov_b64_e32 v[58:59], 0
	v_mov_b64_e32 v[60:61], 0
	v_mov_b64_e32 v[62:63], 0
	s_branch .LBB0_875

.LBB0_882:
	s_mul_hi_u32 s98, s3, 0xba2e8ba3
	s_lshr_b32 s98, s98, 3
	s_mul_i32 s99, s98, 11
	s_sub_u32 s99, s3, s99
	s_and_b32 s100, s90, 1
	s_lshl_b32 s98, s98, 1
	s_or_b32 s98, s98, s100
	s_lshr_b32 s100, s90, 1
	s_lshl_b32 s99, s99, 2
	s_or_b32 s99, s99, s100
	s_and_b32 s101, s98, 7
	s_lshr_b32 s98, s98, 3
	s_mul_i32 s99, s99, 17
	s_add_u32 s98, s98, s99
	s_lshl_b32 s99, s98, 3
	s_or_b32 s99, s99, s101
	s_mul_hi_i32 s10, s98, 0x78787879
	s_lshr_b32 s11, s10, 31
	s_ashr_i32 s10, s10, 3
	s_add_i32 s10, s10, s11
	s_mul_i32 s11, s10, 0xffffffef
	s_add_i32 s11, s11, s98
	s_lshl_b32 s11, s11, 3
	s_or_b32 s12, s11, s101
	v_mov_b32_e32 v0, v174
	s_ashr_i32 s13, s12, 31
	s_lshl_b64 s[34:35], s[12:13], 18
	v_bfe_u32 v2, v0, 1, 3
	v_lshrrev_b32_e32 v3, 4, v0
	v_bfe_u32 v4, v0, 4, 2
	v_lshlrev_b32_e32 v5, 7, v0
	v_and_b32_e32 v6, 0x780, v5
	v_bitop3_b32 v3, v3, v2, 3 bitop3:0x6c
	v_bitop3_b32 v2, v4, v2, 4 bitop3:0x36
	s_add_u32 s34, s38, s34
	v_lshl_or_b32 v7, v3, 4, v6
	v_lshl_or_b32 v6, v2, 4, v6
	v_lshlrev_b32_e32 v2, 6, v0
	s_addc_u32 s35, s39, s35
	s_ashr_i32 s11, s10, 31
	v_lshlrev_b32_e32 v1, 8, v0
	v_and_b32_e32 v8, 0xffffe000, v2
	v_lshlrev_b32_e32 v2, 4, v0
	s_lshl_b64 s[84:85], s[10:11], 18
	v_and_b32_e32 v1, 0xfffff800, v1
	v_xor_b32_e32 v0, v2, v0
	s_movk_i32 s11, 0x70
	v_add_u32_e32 v100, 0, v2
	v_and_or_b32 v64, v0, s11, v1
	v_readfirstlane_b32 s11, v100
	v_add_u32_e32 v101, 0x1000, v100
	s_mov_b32 m0, s11
	v_readfirstlane_b32 s11, v101
	v_add_u32_e32 v102, 0x2000, v100
	global_load_lds_dwordx4 v64, s[34:35]
	v_add_u32_e32 v0, 0x10000, v64
	s_mov_b32 m0, s11
	v_readfirstlane_b32 s11, v102
	v_add_u32_e32 v103, 0x3000, v100
	global_load_lds_dwordx4 v0, s[34:35]
	v_add_u32_e32 v2, 0x20000, v64
	s_mov_b32 m0, s11
	v_readfirstlane_b32 s11, v103
	v_add_u32_e32 v104, 0x4000, v100
	s_add_u32 s88, s92, s84
	global_load_lds_dwordx4 v2, s[34:35]
	v_add_u32_e32 v4, 0x30000, v64
	s_mov_b32 m0, s11
	v_readfirstlane_b32 s11, v104
	v_add_u32_e32 v105, 0x5000, v100
	s_addc_u32 s89, s93, s85
	global_load_lds_dwordx4 v4, s[34:35]
	s_mov_b32 m0, s11
	v_readfirstlane_b32 s11, v105
	v_add_u32_e32 v106, 0x6000, v100
	global_load_lds_dwordx4 v64, s[88:89]
	s_mov_b32 m0, s11
	v_readfirstlane_b32 s11, v106
	v_add_u32_e32 v107, 0x7000, v100
	global_load_lds_dwordx4 v0, s[88:89]
	s_mov_b32 m0, s11
	v_readfirstlane_b32 s11, v107
	global_load_lds_dwordx4 v2, s[88:89]
	s_mov_b32 m0, s11
	s_mul_i32 s11, s10, 0x88
	global_load_lds_dwordx4 v4, s[88:89]
	s_sub_i32 s34, s99, s11
	s_ashr_i32 s35, s34, 31
	s_lshl_b64 s[34:35], s[34:35], 18
	s_add_u32 s34, s38, s34
	v_and_b32_e32 v9, 0x2000, v5
	v_mov_b32_e32 v1, v65
	v_mov_b32_e32 v3, v65
	v_mov_b32_e32 v5, v65
	s_addc_u32 s35, s39, s35
	v_lshl_add_u64 v[66:67], s[34:35], 0, v[64:65]
	v_lshl_add_u64 v[68:69], s[34:35], 0, v[0:1]
	v_lshl_add_u64 v[70:71], s[34:35], 0, v[2:3]
	v_lshl_add_u64 v[72:73], s[34:35], 0, v[4:5]
	s_add_u32 s34, s36, s84
	v_add_u32_e32 v8, 0, v8
	v_add_u32_e32 v9, 0, v9
	s_addc_u32 s35, s37, s85
	v_lshl_add_u64 v[74:75], s[34:35], 0, v[64:65]
	v_lshl_add_u64 v[76:77], s[34:35], 0, v[0:1]
	v_lshl_add_u64 v[78:79], s[34:35], 0, v[2:3]
	v_lshl_add_u64 v[80:81], s[34:35], 0, v[4:5]
	s_mov_b64 s[84:85], 0
	v_add_u32_e32 v64, 0x8000, v100
	v_add_u32_e32 v108, 0x9000, v100
	v_add_u32_e32 v109, 0xa000, v100
	v_add_u32_e32 v110, 0xb000, v100
	v_add_u32_e32 v111, 0xc000, v100
	v_add_u32_e32 v112, 0xd000, v100
	v_add_u32_e32 v113, 0xe000, v100
	v_add_u32_e32 v114, 0xf000, v100
	v_add_u32_e32 v115, v8, v7
	v_add_u32_e32 v116, v9, v7
	v_add_u32_e32 v117, v8, v6
	v_add_u32_e32 v118, v9, v6
	s_mov_b32 s11, 0
	v_mov_b32_e32 v0, 0
	v_mov_b32_e32 v2, 0
	v_mov_b32_e32 v4, 0
	v_mov_b64_e32 v[6:7], 0
	v_mov_b64_e32 v[8:9], 0
	v_mov_b64_e32 v[10:11], 0
	v_mov_b64_e32 v[12:13], 0
	v_mov_b64_e32 v[14:15], 0
	v_mov_b64_e32 v[16:17], 0
	v_mov_b64_e32 v[18:19], 0
	v_mov_b64_e32 v[20:21], 0
	v_mov_b64_e32 v[22:23], 0
	v_mov_b64_e32 v[24:25], 0
	v_mov_b64_e32 v[26:27], 0
	v_mov_b64_e32 v[28:29], 0
	v_mov_b64_e32 v[30:31], 0
	v_mov_b64_e32 v[32:33], 0
	v_mov_b64_e32 v[34:35], 0
	v_mov_b64_e32 v[36:37], 0
	v_mov_b64_e32 v[38:39], 0
	v_mov_b64_e32 v[40:41], 0
	v_mov_b64_e32 v[42:43], 0
	v_mov_b64_e32 v[44:45], 0
	v_mov_b64_e32 v[46:47], 0
	v_mov_b64_e32 v[48:49], 0
	v_mov_b64_e32 v[50:51], 0
	v_mov_b64_e32 v[52:53], 0
	v_mov_b64_e32 v[54:55], 0
	v_mov_b64_e32 v[56:57], 0
	v_mov_b64_e32 v[58:59], 0
	v_mov_b64_e32 v[60:61], 0
	v_mov_b64_e32 v[62:63], 0
	s_nop 1
	v_readfirstlane_b32 s84, v66
	v_readfirstlane_b32 s85, v67
	v_readfirstlane_b32 s98, v74
	v_readfirstlane_b32 s99, v75
	v_readfirstlane_b32 s100, v100
	s_nop 1
	s_sub_u32 s84, s84, 0x80
	s_subb_u32 s85, s85, 0
	s_sub_u32 s98, s98, 0x80
	s_subb_u32 s99, s99, 0
	v_subrev_u32_e32 v66, s84, v66
	v_subrev_u32_e32 v68, s84, v68
	v_subrev_u32_e32 v70, s84, v70
	v_subrev_u32_e32 v72, s84, v72
	v_subrev_u32_e32 v74, s98, v74
	v_subrev_u32_e32 v76, s98, v76
	v_subrev_u32_e32 v78, s98, v78
	v_subrev_u32_e32 v80, s98, v80
	s_add_u32 s84, s84, 0x80
	s_addc_u32 s85, s85, 0x0
	s_add_u32 s98, s98, 0x13c0080
	s_addc_u32 s99, s99, 0x0
	s_branch .LBB0_884

.LBB0_1131:
	s_mul_hi_i32 s6, s18, 0x78787879
	s_lshr_b32 s7, s6, 31
	s_ashr_i32 s6, s6, 6
	s_add_i32 s6, s6, s7
	s_mul_i32 s7, s6, 0x88
	s_sub_i32 s8, s18, s7
	v_mov_b32_e32 v0, v174
	s_ashr_i32 s9, s8, 31
	s_lshl_b64 s[10:11], s[8:9], 18
	v_bfe_u32 v2, v0, 1, 3
	v_lshrrev_b32_e32 v3, 4, v0
	v_bfe_u32 v4, v0, 4, 2
	v_lshlrev_b32_e32 v5, 7, v0
	v_and_b32_e32 v6, 0x780, v5
	v_bitop3_b32 v3, v3, v2, 3 bitop3:0x6c
	v_bitop3_b32 v2, v4, v2, 4 bitop3:0x36
	s_add_u32 s10, s38, s10
	v_lshl_or_b32 v7, v3, 4, v6
	v_lshl_or_b32 v6, v2, 4, v6
	v_lshlrev_b32_e32 v2, 6, v0
	s_addc_u32 s11, s39, s11
	s_ashr_i32 s7, s6, 31
	v_lshlrev_b32_e32 v1, 8, v0
	v_and_b32_e32 v8, 0xffffe000, v2
	v_lshlrev_b32_e32 v2, 4, v0
	s_lshl_b64 s[12:13], s[6:7], 18
	v_and_b32_e32 v1, 0xfffff800, v1
	v_xor_b32_e32 v0, v2, v0
	s_movk_i32 s7, 0x70
	v_add_u32_e32 v103, 0, v2
	v_and_or_b32 v64, v0, s7, v1
	v_readfirstlane_b32 s7, v103
	v_add_u32_e32 v104, 0x1000, v103
	s_mov_b32 m0, s7
	v_readfirstlane_b32 s7, v104
	v_add_u32_e32 v105, 0x2000, v103
	global_load_lds_dwordx4 v64, s[10:11]
	v_add_u32_e32 v0, 0x10000, v64
	s_mov_b32 m0, s7
	v_readfirstlane_b32 s7, v105
	v_add_u32_e32 v106, 0x3000, v103
	global_load_lds_dwordx4 v0, s[10:11]
	v_add_u32_e32 v2, 0x20000, v64
	s_mov_b32 m0, s7
	v_readfirstlane_b32 s7, v106
	v_add_u32_e32 v107, 0x4000, v103
	s_add_u32 s12, s36, s12
	global_load_lds_dwordx4 v2, s[10:11]
	v_add_u32_e32 v4, 0x30000, v64
	s_mov_b32 m0, s7
	v_readfirstlane_b32 s7, v107
	s_addc_u32 s13, s37, s13
	global_load_lds_dwordx4 v4, s[10:11]
	s_mov_b32 m0, s7
	v_lshl_add_u64 v[66:67], s[10:11], 0, v[64:65]
	v_lshl_add_u64 v[74:75], s[12:13], 0, v[64:65]
	global_load_lds_dwordx4 v64, s[12:13]
	v_add_u32_e32 v64, 0x5000, v103
	v_add_u32_e32 v108, 0x6000, v103
	v_readfirstlane_b32 s7, v64
	s_mov_b32 m0, s7
	v_readfirstlane_b32 s7, v108
	v_add_u32_e32 v109, 0x7000, v103
	global_load_lds_dwordx4 v0, s[12:13]
	s_mov_b32 m0, s7
	v_readfirstlane_b32 s7, v109
	global_load_lds_dwordx4 v2, s[12:13]
	s_mov_b32 m0, s7
	v_and_b32_e32 v9, 0x2000, v5
	global_load_lds_dwordx4 v4, s[12:13]
	v_mov_b32_e32 v1, v65
	v_lshl_add_u64 v[68:69], s[10:11], 0, v[0:1]
	v_mov_b32_e32 v3, v65
	v_mov_b32_e32 v5, v65
	v_lshl_add_u64 v[76:77], s[12:13], 0, v[0:1]
	v_add_u32_e32 v0, 0, v8
	v_add_u32_e32 v1, 0, v9
	v_lshl_add_u64 v[70:71], s[10:11], 0, v[2:3]
	v_lshl_add_u64 v[72:73], s[10:11], 0, v[4:5]
	v_lshl_add_u64 v[78:79], s[12:13], 0, v[2:3]
	v_lshl_add_u64 v[80:81], s[12:13], 0, v[4:5]
	s_mov_b64 s[10:11], 0
	v_add_u32_e32 v110, 0x8000, v103
	v_add_u32_e32 v111, 0x9000, v103
	v_add_u32_e32 v112, 0xa000, v103
	v_add_u32_e32 v113, 0xb000, v103
	v_add_u32_e32 v114, 0xc000, v103
	v_add_u32_e32 v115, 0xd000, v103
	v_add_u32_e32 v116, 0xe000, v103
	v_add_u32_e32 v117, 0xf000, v103
	v_add_u32_e32 v118, v0, v7
	v_add_u32_e32 v119, v1, v7
	v_add_u32_e32 v120, v0, v6
	v_add_u32_e32 v121, v1, v6
	s_mov_b32 s7, 0
	v_mov_b64_e32 v[0:1], 0
	v_mov_b32_e32 v2, 0
	v_mov_b32_e32 v4, 0
	v_mov_b64_e32 v[6:7], 0
	v_mov_b64_e32 v[8:9], 0
	v_mov_b64_e32 v[10:11], 0
	v_mov_b64_e32 v[12:13], 0
	v_mov_b64_e32 v[14:15], 0
	v_mov_b64_e32 v[16:17], 0
	v_mov_b64_e32 v[18:19], 0
	v_mov_b64_e32 v[20:21], 0
	v_mov_b64_e32 v[22:23], 0
	v_mov_b64_e32 v[24:25], 0
	v_mov_b64_e32 v[26:27], 0
	v_mov_b64_e32 v[28:29], 0
	v_mov_b64_e32 v[30:31], 0
	v_mov_b64_e32 v[32:33], 0
	v_mov_b64_e32 v[34:35], 0
	v_mov_b64_e32 v[36:37], 0
	v_mov_b64_e32 v[38:39], 0
	v_mov_b64_e32 v[40:41], 0
	v_mov_b64_e32 v[42:43], 0
	v_mov_b64_e32 v[44:45], 0
	v_mov_b64_e32 v[46:47], 0
	v_mov_b64_e32 v[48:49], 0
	v_mov_b64_e32 v[50:51], 0
	v_mov_b64_e32 v[52:53], 0
	v_mov_b64_e32 v[54:55], 0
	v_mov_b64_e32 v[56:57], 0
	v_mov_b64_e32 v[58:59], 0
	v_mov_b64_e32 v[60:61], 0
	v_mov_b64_e32 v[62:63], 0
	s_branch .LBB0_1133

.Lto_j_a1:
	s_mul_i32 s98, s98, 17
	s_add_u32 s98, s98, s99
	s_lshl_b32 s99, s98, 3
	s_or_b32 s99, s99, s18
	s_mul_hi_i32 s6, s98, 0x78787879
	s_lshr_b32 s7, s6, 31
	s_ashr_i32 s6, s6, 3
	s_add_i32 s6, s6, s7
	s_mul_i32 s7, s6, 0xffffffef
	s_add_i32 s7, s7, s98
	s_lshl_b32 s7, s7, 3
	s_or_b32 s8, s7, s18
	v_mov_b32_e32 v0, v174
	s_ashr_i32 s9, s8, 31
	s_lshl_b64 s[10:11], s[8:9], 18
	v_bfe_u32 v2, v0, 1, 3
	v_lshrrev_b32_e32 v3, 4, v0
	v_bfe_u32 v4, v0, 4, 2
	v_lshlrev_b32_e32 v5, 7, v0
	v_and_b32_e32 v6, 0x780, v5
	v_bitop3_b32 v3, v3, v2, 3 bitop3:0x6c
	v_bitop3_b32 v2, v4, v2, 4 bitop3:0x36
	s_add_u32 s10, s38, s10
	v_lshl_or_b32 v7, v3, 4, v6
	v_lshl_or_b32 v6, v2, 4, v6
	v_lshlrev_b32_e32 v2, 6, v0
	s_addc_u32 s11, s39, s11
	s_ashr_i32 s7, s6, 31
	v_lshlrev_b32_e32 v1, 8, v0
	v_and_b32_e32 v8, 0xffffe000, v2
	v_lshlrev_b32_e32 v2, 4, v0
	s_lshl_b64 s[12:13], s[6:7], 18
	v_and_b32_e32 v1, 0xfffff800, v1
	v_xor_b32_e32 v0, v2, v0
	s_movk_i32 s7, 0x70
	v_add_u32_e32 v100, 0, v2
	v_and_or_b32 v64, v0, s7, v1
	v_readfirstlane_b32 s7, v100
	v_add_u32_e32 v101, 0x1000, v100
	s_mov_b32 m0, s7
	v_readfirstlane_b32 s7, v101
	v_add_u32_e32 v102, 0x2000, v100
	global_load_lds_dwordx4 v64, s[10:11]
	v_add_u32_e32 v0, 0x10000, v64
	s_mov_b32 m0, s7
	v_readfirstlane_b32 s7, v102
	v_add_u32_e32 v103, 0x3000, v100
	global_load_lds_dwordx4 v0, s[10:11]
	v_add_u32_e32 v2, 0x20000, v64
	s_mov_b32 m0, s7
	v_readfirstlane_b32 s7, v103
	v_add_u32_e32 v104, 0x4000, v100
	s_add_u32 s12, s36, s12
	global_load_lds_dwordx4 v2, s[10:11]
	v_add_u32_e32 v4, 0x30000, v64
	s_mov_b32 m0, s7
	v_readfirstlane_b32 s7, v104
	v_add_u32_e32 v105, 0x5000, v100
	s_addc_u32 s13, s37, s13
	global_load_lds_dwordx4 v4, s[10:11]
	s_mov_b32 m0, s7
	v_readfirstlane_b32 s7, v105
	v_add_u32_e32 v106, 0x6000, v100
	global_load_lds_dwordx4 v64, s[12:13]
	s_mov_b32 m0, s7
	v_readfirstlane_b32 s7, v106
	v_add_u32_e32 v107, 0x7000, v100
	global_load_lds_dwordx4 v0, s[12:13]
	s_mov_b32 m0, s7
	v_readfirstlane_b32 s7, v107
	global_load_lds_dwordx4 v2, s[12:13]
	s_mov_b32 m0, s7
	s_mul_i32 s7, s6, 0x88
	global_load_lds_dwordx4 v4, s[12:13]
	s_sub_i32 s10, s99, s7
	s_ashr_i32 s11, s10, 31
	s_lshl_b64 s[10:11], s[10:11], 18
	v_and_b32_e32 v9, 0x2000, v5
	s_add_u32 s10, s38, s10
	v_mov_b32_e32 v1, v65
	v_mov_b32_e32 v3, v65
	v_mov_b32_e32 v5, v65
	v_add_u32_e32 v8, 0, v8
	v_add_u32_e32 v9, 0, v9
	s_addc_u32 s11, s39, s11
	v_lshl_add_u64 v[66:67], s[12:13], 0, v[64:65]
	v_lshl_add_u64 v[68:69], s[12:13], 0, v[0:1]
	v_lshl_add_u64 v[70:71], s[12:13], 0, v[2:3]
	v_lshl_add_u64 v[72:73], s[12:13], 0, v[4:5]
	v_lshl_add_u64 v[74:75], s[10:11], 0, v[64:65]
	v_lshl_add_u64 v[76:77], s[10:11], 0, v[0:1]
	v_lshl_add_u64 v[78:79], s[10:11], 0, v[2:3]
	v_lshl_add_u64 v[80:81], s[10:11], 0, v[4:5]
	s_mov_b64 s[10:11], 0
	v_add_u32_e32 v64, 0x8000, v100
	v_add_u32_e32 v108, 0x9000, v100
	v_add_u32_e32 v109, 0xa000, v100
	v_add_u32_e32 v110, 0xb000, v100
	v_add_u32_e32 v111, 0xc000, v100
	v_add_u32_e32 v112, 0xd000, v100
	v_add_u32_e32 v113, 0xe000, v100
	v_add_u32_e32 v114, 0xf000, v100
	v_add_u32_e32 v115, v8, v7
	v_add_u32_e32 v116, v9, v7
	v_add_u32_e32 v117, v8, v6
	v_add_u32_e32 v118, v9, v6
	s_mov_b32 s7, 0
	v_mov_b32_e32 v0, 0
	v_mov_b32_e32 v2, 0
	v_mov_b32_e32 v4, 0
	v_mov_b64_e32 v[6:7], 0
	v_mov_b64_e32 v[8:9], 0
	v_mov_b64_e32 v[10:11], 0
	v_mov_b64_e32 v[12:13], 0
	v_mov_b64_e32 v[14:15], 0
	v_mov_b64_e32 v[16:17], 0
	v_mov_b64_e32 v[18:19], 0
	v_mov_b64_e32 v[20:21], 0
	v_mov_b64_e32 v[22:23], 0
	v_mov_b64_e32 v[24:25], 0
	v_mov_b64_e32 v[26:27], 0
	v_mov_b64_e32 v[28:29], 0
	v_mov_b64_e32 v[30:31], 0
	v_mov_b64_e32 v[32:33], 0
	v_mov_b64_e32 v[34:35], 0
	v_mov_b64_e32 v[36:37], 0
	v_mov_b64_e32 v[38:39], 0
	v_mov_b64_e32 v[40:41], 0
	v_mov_b64_e32 v[42:43], 0
	v_mov_b64_e32 v[44:45], 0
	v_mov_b64_e32 v[46:47], 0
	v_mov_b64_e32 v[48:49], 0
	v_mov_b64_e32 v[50:51], 0
	v_mov_b64_e32 v[52:53], 0
	v_mov_b64_e32 v[54:55], 0
	v_mov_b64_e32 v[56:57], 0
	v_mov_b64_e32 v[58:59], 0
	v_mov_b64_e32 v[60:61], 0
	v_mov_b64_e32 v[62:63], 0
	s_nop 1
	v_readfirstlane_b32 s10, v74
	v_readfirstlane_b32 s11, v75
	v_readfirstlane_b32 s98, v66
	v_readfirstlane_b32 s99, v67
	v_readfirstlane_b32 s100, v100
	s_nop 1
	s_sub_u32 s10, s10, 0x80
	s_subb_u32 s11, s11, 0
	s_sub_u32 s98, s98, 0x80
	s_subb_u32 s99, s99, 0
	v_subrev_u32_e32 v74, s10, v74
	v_subrev_u32_e32 v76, s10, v76
	v_subrev_u32_e32 v78, s10, v78
	v_subrev_u32_e32 v80, s10, v80
	v_subrev_u32_e32 v66, s98, v66
	v_subrev_u32_e32 v68, s98, v68
	v_subrev_u32_e32 v70, s98, v70
	v_subrev_u32_e32 v72, s98, v72
	s_add_u32 s10, s10, 0x80
	s_addc_u32 s11, s11, 0x0
	s_add_u32 s98, s98, 0x80
	s_addc_u32 s99, s99, 0x0
	s_branch .LBB0_1142

.LBB0_1582:
	s_mul_hi_i32 s10, s24, 0x78787879
	s_lshr_b32 s11, s10, 31
	s_ashr_i32 s10, s10, 6
	s_add_i32 s10, s10, s11
	s_mul_i32 s11, s10, 0x88
	v_mov_b32_e32 v0, v174
	s_sub_i32 s12, s24, s11
	s_ashr_i32 s13, s12, 31
	v_bfe_u32 v2, v0, 1, 3
	v_lshrrev_b32_e32 v3, 4, v0
	v_bfe_u32 v4, v0, 4, 2
	v_lshlrev_b32_e32 v5, 7, v0
	v_and_b32_e32 v6, 0x780, v5
	v_bitop3_b32 v3, v3, v2, 3 bitop3:0x6c
	v_bitop3_b32 v2, v4, v2, 4 bitop3:0x36
	s_lshl_b64 s[16:17], s[12:13], 18
	v_lshl_or_b32 v7, v3, 4, v6
	v_lshl_or_b32 v6, v2, 4, v6
	v_lshlrev_b32_e32 v2, 6, v0
	s_add_u32 s16, s38, s16
	v_and_b32_e32 v8, 0xffffe000, v2
	v_lshlrev_b32_e32 v2, 4, v0
	s_addc_u32 s17, s39, s17
	s_ashr_i32 s11, s10, 31
	v_lshlrev_b32_e32 v1, 8, v0
	v_add_u32_e32 v103, 0, v2
	s_lshl_b64 s[18:19], s[10:11], 18
	v_and_b32_e32 v1, 0xfffff800, v1
	v_xor_b32_e32 v0, v2, v0
	v_readfirstlane_b32 s11, v103
	v_add_u32_e32 v104, 0x1000, v103
	v_and_or_b32 v64, v0, s21, v1
	s_mov_b32 m0, s11
	v_readfirstlane_b32 s11, v104
	v_add_u32_e32 v105, 0x2000, v103
	global_load_lds_dwordx4 v64, s[16:17]
	v_add_u32_e32 v0, 0x10000, v64
	s_mov_b32 m0, s11
	v_readfirstlane_b32 s11, v105
	v_add_u32_e32 v106, 0x3000, v103
	global_load_lds_dwordx4 v0, s[16:17]
	v_add_u32_e32 v2, 0x20000, v64
	s_mov_b32 m0, s11
	v_readfirstlane_b32 s11, v106
	v_add_u32_e32 v107, 0x4000, v103
	s_add_u32 s26, s3, s18
	global_load_lds_dwordx4 v2, s[16:17]
	v_add_u32_e32 v4, 0x30000, v64
	s_mov_b32 m0, s11
	v_readfirstlane_b32 s11, v107
	v_add_u32_e32 v108, 0x5000, v103
	s_addc_u32 s27, s20, s19
	global_load_lds_dwordx4 v4, s[16:17]
	s_mov_b32 m0, s11
	v_readfirstlane_b32 s11, v108
	v_add_u32_e32 v109, 0x6000, v103
	global_load_lds_dwordx4 v64, s[26:27]
	s_mov_b32 m0, s11
	v_readfirstlane_b32 s11, v109
	v_add_u32_e32 v110, 0x7000, v103
	global_load_lds_dwordx4 v0, s[26:27]
	s_mov_b32 m0, s11
	v_readfirstlane_b32 s11, v110
	global_load_lds_dwordx4 v2, s[26:27]
	s_mov_b32 m0, s11
	v_and_b32_e32 v9, 0x2000, v5
	global_load_lds_dwordx4 v4, s[26:27]
	v_mov_b32_e32 v1, v65
	v_mov_b32_e32 v3, v65
	v_mov_b32_e32 v5, v65
	v_lshl_add_u64 v[66:67], s[16:17], 0, v[64:65]
	v_lshl_add_u64 v[68:69], s[16:17], 0, v[0:1]
	v_lshl_add_u64 v[70:71], s[16:17], 0, v[2:3]
	v_lshl_add_u64 v[72:73], s[16:17], 0, v[4:5]
	s_add_u32 s16, s36, s18
	v_add_u32_e32 v8, 0, v8
	v_add_u32_e32 v9, 0, v9
	s_addc_u32 s17, s37, s19
	v_lshl_add_u64 v[74:75], s[16:17], 0, v[64:65]
	v_lshl_add_u64 v[76:77], s[16:17], 0, v[0:1]
	v_lshl_add_u64 v[78:79], s[16:17], 0, v[2:3]
	v_lshl_add_u64 v[80:81], s[16:17], 0, v[4:5]
	s_mov_b64 s[16:17], 0
	v_add_u32_e32 v64, 0x8000, v103
	v_add_u32_e32 v111, 0x9000, v103
	v_add_u32_e32 v112, 0xa000, v103
	v_add_u32_e32 v113, 0xb000, v103
	v_add_u32_e32 v114, 0xc000, v103
	v_add_u32_e32 v115, 0xd000, v103
	v_add_u32_e32 v116, 0xe000, v103
	v_add_u32_e32 v117, 0xf000, v103
	v_add_u32_e32 v118, v8, v7
	v_add_u32_e32 v119, v9, v7
	v_add_u32_e32 v120, v8, v6
	v_add_u32_e32 v121, v9, v6
	s_mov_b32 s11, 0
	v_mov_b32_e32 v0, 0
	v_mov_b32_e32 v2, 0
	v_mov_b32_e32 v4, 0
	v_mov_b64_e32 v[6:7], 0
	v_mov_b64_e32 v[8:9], 0
	v_mov_b64_e32 v[10:11], 0
	v_mov_b64_e32 v[12:13], 0
	v_mov_b64_e32 v[14:15], 0
	v_mov_b64_e32 v[16:17], 0
	v_mov_b64_e32 v[18:19], 0
	v_mov_b64_e32 v[20:21], 0
	v_mov_b64_e32 v[22:23], 0
	v_mov_b64_e32 v[24:25], 0
	v_mov_b64_e32 v[26:27], 0
	v_mov_b64_e32 v[28:29], 0
	v_mov_b64_e32 v[30:31], 0
	v_mov_b64_e32 v[32:33], 0
	v_mov_b64_e32 v[34:35], 0
	v_mov_b64_e32 v[36:37], 0
	v_mov_b64_e32 v[38:39], 0
	v_mov_b64_e32 v[40:41], 0
	v_mov_b64_e32 v[42:43], 0
	v_mov_b64_e32 v[44:45], 0
	v_mov_b64_e32 v[46:47], 0
	v_mov_b64_e32 v[48:49], 0
	v_mov_b64_e32 v[50:51], 0
	v_mov_b64_e32 v[52:53], 0
	v_mov_b64_e32 v[54:55], 0
	v_mov_b64_e32 v[56:57], 0
	v_mov_b64_e32 v[58:59], 0
	v_mov_b64_e32 v[60:61], 0
	v_mov_b64_e32 v[62:63], 0
	s_branch .LBB0_1584

.LBB0_1591:
	s_lshr_b32 s98, s3, 3
	s_and_b32 s99, s3, 7
	s_and_b32 s100, s20, 1
	s_lshl_b32 s98, s98, 1
	s_or_b32 s98, s98, s100
	s_lshr_b32 s100, s20, 1
	s_lshl_b32 s99, s99, 2
	s_or_b32 s99, s99, s100
	s_and_b32 s101, s98, 7
	s_lshr_b32 s98, s98, 3
	s_mul_i32 s99, s99, 17
	s_add_u32 s98, s98, s99
	s_lshl_b32 s99, s98, 3
	s_or_b32 s99, s99, s101
	s_mul_hi_i32 s10, s98, 0x78787879
	s_lshr_b32 s11, s10, 31
	s_ashr_i32 s10, s10, 3
	s_add_i32 s10, s10, s11
	s_mul_i32 s11, s10, 0xffffffef
	s_add_i32 s11, s11, s98
	s_lshl_b32 s11, s11, 3
	v_mov_b32_e32 v0, v174
	s_or_b32 s12, s11, s101
	s_ashr_i32 s13, s12, 31
	v_bfe_u32 v2, v0, 1, 3
	v_lshrrev_b32_e32 v3, 4, v0
	v_bfe_u32 v4, v0, 4, 2
	v_lshlrev_b32_e32 v5, 7, v0
	v_and_b32_e32 v6, 0x780, v5
	v_bitop3_b32 v3, v3, v2, 3 bitop3:0x6c
	v_bitop3_b32 v2, v4, v2, 4 bitop3:0x36
	s_lshl_b64 s[16:17], s[12:13], 18
	v_lshl_or_b32 v7, v3, 4, v6
	v_lshl_or_b32 v6, v2, 4, v6
	v_lshlrev_b32_e32 v2, 6, v0
	s_add_u32 s16, s38, s16
	v_and_b32_e32 v8, 0xffffe000, v2
	v_lshlrev_b32_e32 v2, 4, v0
	s_addc_u32 s17, s39, s17
	s_ashr_i32 s11, s10, 31
	v_lshlrev_b32_e32 v1, 8, v0
	v_add_u32_e32 v100, 0, v2
	s_lshl_b64 s[18:19], s[10:11], 18
	v_and_b32_e32 v1, 0xfffff800, v1
	v_xor_b32_e32 v0, v2, v0
	v_readfirstlane_b32 s11, v100
	v_add_u32_e32 v101, 0x1000, v100
	v_and_or_b32 v64, v0, s27, v1
	s_mov_b32 m0, s11
	v_readfirstlane_b32 s11, v101
	v_add_u32_e32 v102, 0x2000, v100
	global_load_lds_dwordx4 v64, s[16:17]
	v_add_u32_e32 v0, 0x10000, v64
	s_mov_b32 m0, s11
	v_readfirstlane_b32 s11, v102
	v_add_u32_e32 v103, 0x3000, v100
	global_load_lds_dwordx4 v0, s[16:17]
	v_add_u32_e32 v2, 0x20000, v64
	s_mov_b32 m0, s11
	v_readfirstlane_b32 s11, v103
	v_add_u32_e32 v104, 0x4000, v100
	s_add_u32 s34, s24, s18
	global_load_lds_dwordx4 v2, s[16:17]
	v_add_u32_e32 v4, 0x30000, v64
	s_mov_b32 m0, s11
	v_readfirstlane_b32 s11, v104
	v_add_u32_e32 v105, 0x5000, v100
	s_addc_u32 s35, s25, s19
	global_load_lds_dwordx4 v4, s[16:17]
	s_mov_b32 m0, s11
	v_readfirstlane_b32 s11, v105
	v_add_u32_e32 v106, 0x6000, v100
	global_load_lds_dwordx4 v64, s[34:35]
	s_mov_b32 m0, s11
	v_readfirstlane_b32 s11, v106
	v_add_u32_e32 v107, 0x7000, v100
	global_load_lds_dwordx4 v0, s[34:35]
	s_mov_b32 m0, s11
	v_readfirstlane_b32 s11, v107
	global_load_lds_dwordx4 v2, s[34:35]
	s_mov_b32 m0, s11
	s_mul_i32 s11, s10, 0x88
	global_load_lds_dwordx4 v4, s[34:35]
	s_sub_i32 s16, s99, s11
	s_ashr_i32 s17, s16, 31
	s_lshl_b64 s[16:17], s[16:17], 18
	s_add_u32 s16, s38, s16
	v_and_b32_e32 v9, 0x2000, v5
	v_mov_b32_e32 v1, v65
	v_mov_b32_e32 v3, v65
	v_mov_b32_e32 v5, v65
	s_addc_u32 s17, s39, s17
	v_lshl_add_u64 v[66:67], s[16:17], 0, v[64:65]
	v_lshl_add_u64 v[68:69], s[16:17], 0, v[0:1]
	v_lshl_add_u64 v[70:71], s[16:17], 0, v[2:3]
	v_lshl_add_u64 v[72:73], s[16:17], 0, v[4:5]
	s_add_u32 s16, s36, s18
	v_add_u32_e32 v8, 0, v8
	v_add_u32_e32 v9, 0, v9
	s_addc_u32 s17, s37, s19
	v_lshl_add_u64 v[74:75], s[16:17], 0, v[64:65]
	v_lshl_add_u64 v[76:77], s[16:17], 0, v[0:1]
	v_lshl_add_u64 v[78:79], s[16:17], 0, v[2:3]
	v_lshl_add_u64 v[80:81], s[16:17], 0, v[4:5]
	s_mov_b64 s[16:17], 0
	v_add_u32_e32 v64, 0x8000, v100
	v_add_u32_e32 v108, 0x9000, v100
	v_add_u32_e32 v109, 0xa000, v100
	v_add_u32_e32 v110, 0xb000, v100
	v_add_u32_e32 v111, 0xc000, v100
	v_add_u32_e32 v112, 0xd000, v100
	v_add_u32_e32 v113, 0xe000, v100
	v_add_u32_e32 v114, 0xf000, v100
	v_add_u32_e32 v115, v8, v7
	v_add_u32_e32 v116, v9, v7
	v_add_u32_e32 v117, v8, v6
	v_add_u32_e32 v118, v9, v6
	s_mov_b32 s11, 0
	v_mov_b32_e32 v0, 0
	v_mov_b32_e32 v2, 0
	v_mov_b32_e32 v4, 0
	v_mov_b64_e32 v[6:7], 0
	v_mov_b64_e32 v[8:9], 0
	v_mov_b64_e32 v[10:11], 0
	v_mov_b64_e32 v[12:13], 0
	v_mov_b64_e32 v[14:15], 0
	v_mov_b64_e32 v[16:17], 0
	v_mov_b64_e32 v[18:19], 0
	v_mov_b64_e32 v[20:21], 0
	v_mov_b64_e32 v[22:23], 0
	v_mov_b64_e32 v[24:25], 0
	v_mov_b64_e32 v[26:27], 0
	v_mov_b64_e32 v[28:29], 0
	v_mov_b64_e32 v[30:31], 0
	v_mov_b64_e32 v[32:33], 0
	v_mov_b64_e32 v[34:35], 0
	v_mov_b64_e32 v[36:37], 0
	v_mov_b64_e32 v[38:39], 0
	v_mov_b64_e32 v[40:41], 0
	v_mov_b64_e32 v[42:43], 0
	v_mov_b64_e32 v[44:45], 0
	v_mov_b64_e32 v[46:47], 0
	v_mov_b64_e32 v[48:49], 0
	v_mov_b64_e32 v[50:51], 0
	v_mov_b64_e32 v[52:53], 0
	v_mov_b64_e32 v[54:55], 0
	v_mov_b64_e32 v[56:57], 0
	v_mov_b64_e32 v[58:59], 0
	v_mov_b64_e32 v[60:61], 0
	v_mov_b64_e32 v[62:63], 0
	s_nop 1
	v_readfirstlane_b32 s16, v66
	v_readfirstlane_b32 s17, v67
	v_readfirstlane_b32 s98, v74
	v_readfirstlane_b32 s99, v75
	v_readfirstlane_b32 s100, v100
	s_nop 1
	s_sub_u32 s16, s16, 0x80
	s_subb_u32 s17, s17, 0
	s_sub_u32 s98, s98, 0x80
	s_subb_u32 s99, s99, 0
	v_subrev_u32_e32 v66, s16, v66
	v_subrev_u32_e32 v68, s16, v68
	v_subrev_u32_e32 v70, s16, v70
	v_subrev_u32_e32 v72, s16, v72
	v_subrev_u32_e32 v74, s98, v74
	v_subrev_u32_e32 v76, s98, v76
	v_subrev_u32_e32 v78, s98, v78
	v_subrev_u32_e32 v80, s98, v80
	s_add_u32 s16, s16, 0x80
	s_addc_u32 s17, s17, 0x0
	s_add_u32 s98, s98, 0x7c0080
	s_addc_u32 s99, s99, 0x0
	s_branch .LBB0_1593

.LBB0_1856:
	s_mul_hi_i32 s10, s23, 0x78787879
	s_lshr_b32 s11, s10, 31
	s_ashr_i32 s10, s10, 6
	s_add_i32 s10, s10, s11
	s_mul_i32 s11, s10, 0x88
	v_mov_b32_e32 v0, v174
	s_sub_i32 s12, s23, s11
	s_ashr_i32 s13, s12, 31
	v_bfe_u32 v2, v0, 1, 3
	v_lshrrev_b32_e32 v3, 4, v0
	v_bfe_u32 v4, v0, 4, 2
	v_lshlrev_b32_e32 v5, 7, v0
	v_and_b32_e32 v6, 0x780, v5
	v_bitop3_b32 v3, v3, v2, 3 bitop3:0x6c
	v_bitop3_b32 v2, v4, v2, 4 bitop3:0x36
	s_lshl_b64 s[16:17], s[12:13], 18
	v_lshl_or_b32 v7, v3, 4, v6
	v_lshl_or_b32 v6, v2, 4, v6
	v_lshlrev_b32_e32 v2, 6, v0
	s_add_u32 s16, s38, s16
	v_and_b32_e32 v8, 0xffffe000, v2
	v_lshlrev_b32_e32 v2, 4, v0
	s_addc_u32 s17, s39, s17
	s_ashr_i32 s11, s10, 31
	v_lshlrev_b32_e32 v1, 8, v0
	v_add_u32_e32 v103, 0, v2
	s_lshl_b64 s[18:19], s[10:11], 18
	v_and_b32_e32 v1, 0xfffff800, v1
	v_xor_b32_e32 v0, v2, v0
	v_readfirstlane_b32 s11, v103
	v_add_u32_e32 v104, 0x1000, v103
	v_and_or_b32 v64, v0, s21, v1
	s_mov_b32 m0, s11
	v_readfirstlane_b32 s11, v104
	v_add_u32_e32 v105, 0x2000, v103
	global_load_lds_dwordx4 v64, s[16:17]
	v_add_u32_e32 v0, 0x10000, v64
	s_mov_b32 m0, s11
	v_readfirstlane_b32 s11, v105
	v_add_u32_e32 v106, 0x3000, v103
	global_load_lds_dwordx4 v0, s[16:17]
	v_add_u32_e32 v2, 0x20000, v64
	s_mov_b32 m0, s11
	v_readfirstlane_b32 s11, v106
	v_add_u32_e32 v107, 0x4000, v103
	s_add_u32 s24, s3, s18
	global_load_lds_dwordx4 v2, s[16:17]
	v_add_u32_e32 v4, 0x30000, v64
	s_mov_b32 m0, s11
	v_readfirstlane_b32 s11, v107
	v_add_u32_e32 v108, 0x5000, v103
	s_addc_u32 s25, s20, s19
	global_load_lds_dwordx4 v4, s[16:17]
	s_mov_b32 m0, s11
	v_readfirstlane_b32 s11, v108
	v_add_u32_e32 v109, 0x6000, v103
	global_load_lds_dwordx4 v64, s[24:25]
	s_mov_b32 m0, s11
	v_readfirstlane_b32 s11, v109
	v_add_u32_e32 v110, 0x7000, v103
	global_load_lds_dwordx4 v0, s[24:25]
	s_mov_b32 m0, s11
	v_readfirstlane_b32 s11, v110
	global_load_lds_dwordx4 v2, s[24:25]
	s_mov_b32 m0, s11
	v_and_b32_e32 v9, 0x2000, v5
	global_load_lds_dwordx4 v4, s[24:25]
	v_mov_b32_e32 v1, v65
	v_mov_b32_e32 v3, v65
	v_mov_b32_e32 v5, v65
	v_lshl_add_u64 v[66:67], s[16:17], 0, v[64:65]
	v_lshl_add_u64 v[68:69], s[16:17], 0, v[0:1]
	v_lshl_add_u64 v[70:71], s[16:17], 0, v[2:3]
	v_lshl_add_u64 v[72:73], s[16:17], 0, v[4:5]
	s_add_u32 s16, s36, s18
	v_add_u32_e32 v8, 0, v8
	v_add_u32_e32 v9, 0, v9
	s_addc_u32 s17, s37, s19
	v_lshl_add_u64 v[74:75], s[16:17], 0, v[64:65]
	v_lshl_add_u64 v[76:77], s[16:17], 0, v[0:1]
	v_lshl_add_u64 v[78:79], s[16:17], 0, v[2:3]
	v_lshl_add_u64 v[80:81], s[16:17], 0, v[4:5]
	s_mov_b64 s[16:17], 0
	v_add_u32_e32 v64, 0x8000, v103
	v_add_u32_e32 v111, 0x9000, v103
	v_add_u32_e32 v112, 0xa000, v103
	v_add_u32_e32 v113, 0xb000, v103
	v_add_u32_e32 v114, 0xc000, v103
	v_add_u32_e32 v115, 0xd000, v103
	v_add_u32_e32 v116, 0xe000, v103
	v_add_u32_e32 v117, 0xf000, v103
	v_add_u32_e32 v118, v8, v7
	v_add_u32_e32 v119, v9, v7
	v_add_u32_e32 v120, v8, v6
	v_add_u32_e32 v121, v9, v6
	s_mov_b32 s11, 0
	v_mov_b32_e32 v0, 0
	v_mov_b32_e32 v2, 0
	v_mov_b32_e32 v4, 0
	v_mov_b64_e32 v[6:7], 0
	v_mov_b64_e32 v[8:9], 0
	v_mov_b64_e32 v[10:11], 0
	v_mov_b64_e32 v[12:13], 0
	v_mov_b64_e32 v[14:15], 0
	v_mov_b64_e32 v[16:17], 0
	v_mov_b64_e32 v[18:19], 0
	v_mov_b64_e32 v[20:21], 0
	v_mov_b64_e32 v[22:23], 0
	v_mov_b64_e32 v[24:25], 0
	v_mov_b64_e32 v[26:27], 0
	v_mov_b64_e32 v[28:29], 0
	v_mov_b64_e32 v[30:31], 0
	v_mov_b64_e32 v[32:33], 0
	v_mov_b64_e32 v[34:35], 0
	v_mov_b64_e32 v[36:37], 0
	v_mov_b64_e32 v[38:39], 0
	v_mov_b64_e32 v[40:41], 0
	v_mov_b64_e32 v[42:43], 0
	v_mov_b64_e32 v[44:45], 0
	v_mov_b64_e32 v[46:47], 0
	v_mov_b64_e32 v[48:49], 0
	v_mov_b64_e32 v[50:51], 0
	v_mov_b64_e32 v[52:53], 0
	v_mov_b64_e32 v[54:55], 0
	v_mov_b64_e32 v[56:57], 0
	v_mov_b64_e32 v[58:59], 0
	v_mov_b64_e32 v[60:61], 0
	v_mov_b64_e32 v[62:63], 0
	s_branch .LBB0_1858

.LBB0_1865:
	s_mul_hi_u32 s98, s3, 0xba2e8ba3
	s_lshr_b32 s98, s98, 3
	s_mul_i32 s99, s98, 11
	s_sub_u32 s99, s3, s99
	s_and_b32 s100, s20, 1
	s_lshl_b32 s98, s98, 1
	s_or_b32 s98, s98, s100
	s_lshr_b32 s100, s20, 1
	s_lshl_b32 s99, s99, 2
	s_or_b32 s99, s99, s100
	s_and_b32 s101, s98, 7
	s_lshr_b32 s98, s98, 3
	s_mul_i32 s99, s99, 17
	s_add_u32 s98, s98, s99
	s_lshl_b32 s99, s98, 3
	s_or_b32 s99, s99, s101
	s_mul_hi_i32 s10, s98, 0x78787879
	s_lshr_b32 s11, s10, 31
	s_ashr_i32 s10, s10, 3
	s_add_i32 s10, s10, s11
	s_mul_i32 s11, s10, 0xffffffef
	s_add_i32 s11, s11, s98
	s_lshl_b32 s11, s11, 3
	v_mov_b32_e32 v0, v174
	s_or_b32 s12, s11, s101
	s_ashr_i32 s13, s12, 31
	v_bfe_u32 v2, v0, 1, 3
	v_lshrrev_b32_e32 v3, 4, v0
	v_bfe_u32 v4, v0, 4, 2
	v_lshlrev_b32_e32 v5, 7, v0
	v_and_b32_e32 v6, 0x780, v5
	v_bitop3_b32 v3, v3, v2, 3 bitop3:0x6c
	v_bitop3_b32 v2, v4, v2, 4 bitop3:0x36
	s_lshl_b64 s[16:17], s[12:13], 18
	v_lshl_or_b32 v7, v3, 4, v6
	v_lshl_or_b32 v6, v2, 4, v6
	v_lshlrev_b32_e32 v2, 6, v0
	s_add_u32 s16, s38, s16
	v_and_b32_e32 v8, 0xffffe000, v2
	v_lshlrev_b32_e32 v2, 4, v0
	s_addc_u32 s17, s39, s17
	s_ashr_i32 s11, s10, 31
	v_lshlrev_b32_e32 v1, 8, v0
	v_add_u32_e32 v100, 0, v2
	s_lshl_b64 s[18:19], s[10:11], 18
	v_and_b32_e32 v1, 0xfffff800, v1
	v_xor_b32_e32 v0, v2, v0
	v_readfirstlane_b32 s11, v100
	v_add_u32_e32 v101, 0x1000, v100
	v_and_or_b32 v64, v0, s25, v1
	s_mov_b32 m0, s11
	v_readfirstlane_b32 s11, v101
	v_add_u32_e32 v102, 0x2000, v100
	global_load_lds_dwordx4 v64, s[16:17]
	v_add_u32_e32 v0, 0x10000, v64
	s_mov_b32 m0, s11
	v_readfirstlane_b32 s11, v102
	v_add_u32_e32 v103, 0x3000, v100
	global_load_lds_dwordx4 v0, s[16:17]
	v_add_u32_e32 v2, 0x20000, v64
	s_mov_b32 m0, s11
	v_readfirstlane_b32 s11, v103
	v_add_u32_e32 v104, 0x4000, v100
	s_add_u32 s34, s22, s18
	global_load_lds_dwordx4 v2, s[16:17]
	v_add_u32_e32 v4, 0x30000, v64
	s_mov_b32 m0, s11
	v_readfirstlane_b32 s11, v104
	v_add_u32_e32 v105, 0x5000, v100
	s_addc_u32 s35, s23, s19
	global_load_lds_dwordx4 v4, s[16:17]
	s_mov_b32 m0, s11
	v_readfirstlane_b32 s11, v105
	v_add_u32_e32 v106, 0x6000, v100
	global_load_lds_dwordx4 v64, s[34:35]
	s_mov_b32 m0, s11
	v_readfirstlane_b32 s11, v106
	v_add_u32_e32 v107, 0x7000, v100
	global_load_lds_dwordx4 v0, s[34:35]
	s_mov_b32 m0, s11
	v_readfirstlane_b32 s11, v107
	global_load_lds_dwordx4 v2, s[34:35]
	s_mov_b32 m0, s11
	s_mul_i32 s11, s10, 0x88
	global_load_lds_dwordx4 v4, s[34:35]
	s_sub_i32 s16, s99, s11
	s_ashr_i32 s17, s16, 31
	s_lshl_b64 s[16:17], s[16:17], 18
	s_add_u32 s16, s38, s16
	v_and_b32_e32 v9, 0x2000, v5
	v_mov_b32_e32 v1, v65
	v_mov_b32_e32 v3, v65
	v_mov_b32_e32 v5, v65
	s_addc_u32 s17, s39, s17
	v_lshl_add_u64 v[66:67], s[16:17], 0, v[64:65]
	v_lshl_add_u64 v[68:69], s[16:17], 0, v[0:1]
	v_lshl_add_u64 v[70:71], s[16:17], 0, v[2:3]
	v_lshl_add_u64 v[72:73], s[16:17], 0, v[4:5]
	s_add_u32 s16, s36, s18
	v_add_u32_e32 v8, 0, v8
	v_add_u32_e32 v9, 0, v9
	s_addc_u32 s17, s37, s19
	v_lshl_add_u64 v[74:75], s[16:17], 0, v[64:65]
	v_lshl_add_u64 v[76:77], s[16:17], 0, v[0:1]
	v_lshl_add_u64 v[78:79], s[16:17], 0, v[2:3]
	v_lshl_add_u64 v[80:81], s[16:17], 0, v[4:5]
	s_mov_b64 s[16:17], 0
	v_add_u32_e32 v64, 0x8000, v100
	v_add_u32_e32 v108, 0x9000, v100
	v_add_u32_e32 v109, 0xa000, v100
	v_add_u32_e32 v110, 0xb000, v100
	v_add_u32_e32 v111, 0xc000, v100
	v_add_u32_e32 v112, 0xd000, v100
	v_add_u32_e32 v113, 0xe000, v100
	v_add_u32_e32 v114, 0xf000, v100
	v_add_u32_e32 v115, v8, v7
	v_add_u32_e32 v116, v9, v7
	v_add_u32_e32 v117, v8, v6
	v_add_u32_e32 v118, v9, v6
	s_mov_b32 s11, 0
	v_mov_b32_e32 v0, 0
	v_mov_b32_e32 v2, 0
	v_mov_b32_e32 v4, 0
	v_mov_b64_e32 v[6:7], 0
	v_mov_b64_e32 v[8:9], 0
	v_mov_b64_e32 v[10:11], 0
	v_mov_b64_e32 v[12:13], 0
	v_mov_b64_e32 v[14:15], 0
	v_mov_b64_e32 v[16:17], 0
	v_mov_b64_e32 v[18:19], 0
	v_mov_b64_e32 v[20:21], 0
	v_mov_b64_e32 v[22:23], 0
	v_mov_b64_e32 v[24:25], 0
	v_mov_b64_e32 v[26:27], 0
	v_mov_b64_e32 v[28:29], 0
	v_mov_b64_e32 v[30:31], 0
	v_mov_b64_e32 v[32:33], 0
	v_mov_b64_e32 v[34:35], 0
	v_mov_b64_e32 v[36:37], 0
	v_mov_b64_e32 v[38:39], 0
	v_mov_b64_e32 v[40:41], 0
	v_mov_b64_e32 v[42:43], 0
	v_mov_b64_e32 v[44:45], 0
	v_mov_b64_e32 v[46:47], 0
	v_mov_b64_e32 v[48:49], 0
	v_mov_b64_e32 v[50:51], 0
	v_mov_b64_e32 v[52:53], 0
	v_mov_b64_e32 v[54:55], 0
	v_mov_b64_e32 v[56:57], 0
	v_mov_b64_e32 v[58:59], 0
	v_mov_b64_e32 v[60:61], 0
	v_mov_b64_e32 v[62:63], 0
	s_nop 1
	v_readfirstlane_b32 s16, v66
	v_readfirstlane_b32 s17, v67
	v_readfirstlane_b32 s98, v74
	v_readfirstlane_b32 s99, v75
	v_readfirstlane_b32 s100, v100
	s_nop 1
	s_sub_u32 s16, s16, 0x80
	s_subb_u32 s17, s17, 0
	s_sub_u32 s98, s98, 0x80
	s_subb_u32 s99, s99, 0
	v_subrev_u32_e32 v66, s16, v66
	v_subrev_u32_e32 v68, s16, v68
	v_subrev_u32_e32 v70, s16, v70
	v_subrev_u32_e32 v72, s16, v72
	v_subrev_u32_e32 v74, s98, v74
	v_subrev_u32_e32 v76, s98, v76
	v_subrev_u32_e32 v78, s98, v78
	v_subrev_u32_e32 v80, s98, v80
	s_add_u32 s16, s16, 0x80
	s_addc_u32 s17, s17, 0x0
	s_add_u32 s98, s98, 0x13c0080
	s_addc_u32 s99, s99, 0x0
	s_branch .LBB0_1867
